# NSA selected-branch P.V: V fragments read with ds_read_b64 straight into the MFMA operand registers (48 shuffle v_mov per iteration removed), same MFMA order and operands
# speedup vs baseline: 1.0050x; 1.0026x over previous
.LBB0_762:
	v_exp_f32_e32 v2, v120
	v_exp_f32_e32 v3, v121
	v_exp_f32_e32 v112, v112
	v_exp_f32_e32 v113, v113
	v_exp_f32_e32 v120, v122
	v_exp_f32_e32 v121, v123
	v_exp_f32_e32 v122, v132
	v_exp_f32_e32 v123, v133
	v_exp_f32_e32 v132, v134
	v_exp_f32_e32 v133, v135
	v_exp_f32_e32 v116, v116
	v_exp_f32_e32 v117, v117
	v_exp_f32_e32 v118, v118
	v_exp_f32_e32 v119, v119
	v_exp_f32_e32 v134, v114
	v_exp_f32_e32 v135, v115
	v_exp_f32_e32 v140, v140
	v_exp_f32_e32 v141, v141
	v_exp_f32_e32 v142, v142
	v_exp_f32_e32 v143, v143
	v_exp_f32_e32 v136, v136
	v_exp_f32_e32 v137, v137
	v_exp_f32_e32 v138, v138
	v_exp_f32_e32 v139, v139
	v_exp_f32_e32 v155, v124
	v_exp_f32_e32 v177, v125
	v_exp_f32_e32 v178, v126
	v_exp_f32_e32 v179, v127
	v_exp_f32_e32 v180, v128
	v_exp_f32_e32 v181, v129
	v_exp_f32_e32 v182, v130
	v_exp_f32_e32 v183, v131
	v_cvt_pk_bf16_f32 v114, v2, v3
	v_add3_u32 v3, s75, v167, v168
	v_cvt_pk_bf16_f32 v115, v120, v121
	v_cvt_pk_bf16_f32 v120, v112, v113
	v_lshl_add_u32 v112, v169, 1, v3
	v_lshl_add_u32 v113, v170, 1, v3
	v_cvt_pk_bf16_f32 v116, v116, v117
	v_cvt_pk_bf16_f32 v117, v118, v119
	v_cvt_pk_bf16_f32 v118, v122, v123
	v_cvt_pk_bf16_f32 v119, v132, v133
	v_cvt_pk_bf16_f32 v121, v134, v135
	ds_read_b64 v[130:131], v112 offset:8192
	ds_read_b64 v[132:133], v113 offset:8192
	ds_read_b64 v[126:127], v112 offset:10240
	ds_read_b64 v[128:129], v113 offset:10240
	v_lshl_add_u32 v2, v171, 1, v3
	v_lshl_add_u32 v3, v172, 1, v3
	s_andn2_b64 vcc, exec, s[34:35]
	s_waitcnt lgkmcnt(2)
	v_mfma_f32_16x16x32_bf16 v[52:55], v[130:133], v[114:117], v[52:55]
	v_mfma_f32_16x16x32_bf16 v[40:43], v[130:133], v[118:121], v[40:43]
	ds_read_b64 v[122:123], v112 offset:12288
	ds_read_b64 v[124:125], v113 offset:12288
	ds_read_b64 v[130:131], v112 offset:14336
	ds_read_b64 v[132:133], v113 offset:14336
	s_waitcnt lgkmcnt(4)
	v_mfma_f32_16x16x32_bf16 v[48:51], v[126:129], v[114:117], v[48:51]
	v_mfma_f32_16x16x32_bf16 v[32:35], v[126:129], v[118:121], v[32:35]
	s_waitcnt lgkmcnt(2)
	v_mfma_f32_16x16x32_bf16 v[44:47], v[122:125], v[114:117], v[44:47]
	ds_read_b64 v[126:127], v2 offset:8192
	ds_read_b64 v[128:129], v3 offset:8192
	v_mfma_f32_16x16x32_bf16 v[28:31], v[122:125], v[118:121], v[28:31]
	s_waitcnt lgkmcnt(2)
	v_mfma_f32_16x16x32_bf16 v[36:39], v[130:133], v[114:117], v[36:39]
	v_mfma_f32_16x16x32_bf16 v[24:27], v[130:133], v[118:121], v[24:27]
	ds_read_b64 v[122:123], v2 offset:10240
	ds_read_b64 v[124:125], v3 offset:10240
	v_mfma_f32_16x16x32_bf16 v[72:75], v[20:23], v[114:117], v[72:75]
	v_cvt_pk_bf16_f32 v114, v140, v141
	v_cvt_pk_bf16_f32 v115, v142, v143
	v_cvt_pk_bf16_f32 v116, v155, v177
	v_mfma_f32_16x16x32_bf16 v[76:79], v[20:23], v[118:121], v[76:79]
	v_cvt_pk_bf16_f32 v117, v178, v179
	v_cvt_pk_bf16_f32 v118, v136, v137
	v_cvt_pk_bf16_f32 v119, v138, v139
	v_cvt_pk_bf16_f32 v120, v180, v181
	v_cvt_pk_bf16_f32 v121, v182, v183
	s_waitcnt lgkmcnt(2)
	s_nop 0
	v_mfma_f32_16x16x32_bf16 v[52:55], v[126:129], v[114:117], v[52:55]
	v_mfma_f32_16x16x32_bf16 v[40:43], v[126:129], v[118:121], v[40:43]
	ds_read_b64 v[130:131], v2 offset:12288
	ds_read_b64 v[132:133], v3 offset:12288
	ds_read_b64 v[126:127], v2 offset:14336
	ds_read_b64 v[128:129], v3 offset:14336
	s_waitcnt lgkmcnt(4)
	v_mfma_f32_16x16x32_bf16 v[48:51], v[122:125], v[114:117], v[48:51]
	v_mfma_f32_16x16x32_bf16 v[32:35], v[122:125], v[118:121], v[32:35]
	v_mfma_f32_16x16x32_bf16 v[72:75], v[20:23], v[114:117], v[72:75]
	v_mfma_f32_16x16x32_bf16 v[76:79], v[20:23], v[118:121], v[76:79]
	s_waitcnt lgkmcnt(2)
	v_mfma_f32_16x16x32_bf16 v[44:47], v[130:133], v[114:117], v[44:47]
	v_mfma_f32_16x16x32_bf16 v[28:31], v[130:133], v[118:121], v[28:31]
	s_waitcnt lgkmcnt(0)
	v_mfma_f32_16x16x32_bf16 v[36:39], v[126:129], v[114:117], v[36:39]
	v_mfma_f32_16x16x32_bf16 v[24:27], v[126:129], v[118:121], v[24:27]
	s_cbranch_vccnz .LBB0_764
	ds_read_b64 v[130:131], v112 offset:24576
	ds_read_b64 v[132:133], v113 offset:24576
	ds_read_b64 v[126:127], v112 offset:26624
	ds_read_b64 v[128:129], v113 offset:26624
	v_exp_f32_e32 v88, v88
	v_exp_f32_e32 v89, v89
	v_exp_f32_e32 v90, v90
	v_exp_f32_e32 v91, v91
	v_exp_f32_e32 v100, v100
	v_exp_f32_e32 v101, v101
	v_exp_f32_e32 v102, v102
	v_exp_f32_e32 v103, v103
	v_exp_f32_e32 v84, v84
	v_exp_f32_e32 v85, v85
	v_exp_f32_e32 v86, v86
	v_exp_f32_e32 v87, v87
	v_exp_f32_e32 v80, v80
	v_exp_f32_e32 v81, v81
	v_exp_f32_e32 v82, v82
	v_exp_f32_e32 v83, v83
	v_cvt_pk_bf16_f32 v114, v88, v89
	v_cvt_pk_bf16_f32 v115, v90, v91
	v_cvt_pk_bf16_f32 v116, v84, v85
	v_cvt_pk_bf16_f32 v117, v86, v87
	v_cvt_pk_bf16_f32 v118, v100, v101
	v_cvt_pk_bf16_f32 v119, v102, v103
	v_cvt_pk_bf16_f32 v120, v80, v81
	v_cvt_pk_bf16_f32 v121, v82, v83
	s_waitcnt lgkmcnt(2)
	s_nop 0
	v_mfma_f32_16x16x32_bf16 v[52:55], v[130:133], v[114:117], v[52:55]
	v_mfma_f32_16x16x32_bf16 v[40:43], v[130:133], v[118:121], v[40:43]
	ds_read_b64 v[134:135], v112 offset:28672
	ds_read_b64 v[136:137], v113 offset:28672
	ds_read_b64 v[122:123], v112 offset:30720
	ds_read_b64 v[124:125], v113 offset:30720
	v_exp_f32_e32 v108, v108
	v_exp_f32_e32 v109, v109
	v_mfma_f32_16x16x32_bf16 v[76:79], v[20:23], v[118:121], v[76:79]
	v_exp_f32_e32 v110, v110
	v_exp_f32_e32 v111, v111
	v_exp_f32_e32 v104, v104
	s_waitcnt lgkmcnt(4)
	v_mfma_f32_16x16x32_bf16 v[48:51], v[126:129], v[114:117], v[48:51]
	v_exp_f32_e32 v105, v105
	v_exp_f32_e32 v106, v106
	v_exp_f32_e32 v107, v107
	v_mfma_f32_16x16x32_bf16 v[32:35], v[126:129], v[118:121], v[32:35]
	ds_read_b64 v[130:131], v2 offset:24576
	ds_read_b64 v[132:133], v3 offset:24576
	v_exp_f32_e32 v92, v92
	v_exp_f32_e32 v93, v93
	s_waitcnt lgkmcnt(4)
	v_mfma_f32_16x16x32_bf16 v[28:31], v[134:137], v[118:121], v[28:31]
	v_exp_f32_e32 v94, v94
	v_exp_f32_e32 v95, v95
	v_exp_f32_e32 v96, v96
	s_waitcnt lgkmcnt(2)
	v_mfma_f32_16x16x32_bf16 v[24:27], v[122:125], v[118:121], v[24:27]
	ds_read_b64 v[126:127], v2 offset:26624
	ds_read_b64 v[128:129], v3 offset:26624
	v_exp_f32_e32 v97, v97
	v_exp_f32_e32 v98, v98
	v_mfma_f32_16x16x32_bf16 v[36:39], v[122:125], v[114:117], v[36:39]
	v_exp_f32_e32 v99, v99
	v_mfma_f32_16x16x32_bf16 v[72:75], v[20:23], v[114:117], v[72:75]
	v_cvt_pk_bf16_f32 v112, v108, v109
	v_cvt_pk_bf16_f32 v113, v110, v111
	v_cvt_pk_bf16_f32 v118, v96, v97
	v_mfma_f32_16x16x32_bf16 v[44:47], v[134:137], v[114:117], v[44:47]
	v_cvt_pk_bf16_f32 v114, v92, v93
	v_cvt_pk_bf16_f32 v115, v94, v95
	v_cvt_pk_bf16_f32 v116, v104, v105
	v_cvt_pk_bf16_f32 v117, v106, v107
	v_cvt_pk_bf16_f32 v119, v98, v99
	s_waitcnt lgkmcnt(2)
	s_nop 0
	v_mfma_f32_16x16x32_bf16 v[52:55], v[130:133], v[112:115], v[52:55]
	v_mfma_f32_16x16x32_bf16 v[40:43], v[130:133], v[116:119], v[40:43]
	ds_read_b64 v[122:123], v2 offset:28672
	ds_read_b64 v[124:125], v3 offset:28672
	ds_read_b64 v[134:135], v2 offset:30720
	ds_read_b64 v[136:137], v3 offset:30720
	s_waitcnt lgkmcnt(4)
	v_mfma_f32_16x16x32_bf16 v[48:51], v[126:129], v[112:115], v[48:51]
	v_mfma_f32_16x16x32_bf16 v[32:35], v[126:129], v[116:119], v[32:35]
	v_mfma_f32_16x16x32_bf16 v[72:75], v[20:23], v[112:115], v[72:75]
	v_mfma_f32_16x16x32_bf16 v[76:79], v[20:23], v[116:119], v[76:79]
	s_waitcnt lgkmcnt(2)
	v_mfma_f32_16x16x32_bf16 v[44:47], v[122:125], v[112:115], v[44:47]
	v_mfma_f32_16x16x32_bf16 v[28:31], v[122:125], v[116:119], v[28:31]
	s_waitcnt lgkmcnt(0)
	v_mfma_f32_16x16x32_bf16 v[36:39], v[134:137], v[112:115], v[36:39]
	v_mfma_f32_16x16x32_bf16 v[24:27], v[134:137], v[116:119], v[24:27]
